# v68 + phase 0: the four loads of each x row issued together with counted waits (was load/wait/store x4)
# speedup vs baseline: 1.0145x; 1.0086x over previous
.LBB0_25:
	v_add_u32_e32 v2, 0xffffc000, v0
	v_lshlrev_b64 v[24:25], 12, v[2:3]
	v_lshl_add_u64 v[24:25], s[10:11], 0, v[24:25]
	v_cmp_gt_i32_e64 s[6:7], s5, v0
	v_mov_b32_e32 v11, v3
	s_nop 0
	v_cndmask_b32_e64 v25, v25, v7, s[6:7]
	v_cndmask_b32_e64 v24, v24, v6, s[6:7]
	v_lshl_add_u64 v[36:37], v[24:25], 0, v[10:11]
	global_load_dwordx4 v[24:27], v[36:37], off
	global_load_dwordx4 v[28:31], v[36:37], off offset:1024
	global_load_dwordx4 v[32:35], v[36:37], off offset:2048
	global_load_dwordx4 v[36:39], v[36:37], off offset:3072
	v_cmp_lt_i32_e64 s[6:7], v16, v17
	s_waitcnt vmcnt(3)
	v_cvt_pk_bf16_f32 v40, v24, v25
	v_cvt_pk_bf16_f32 v41, v26, v27
	global_store_dwordx2 v[12:13], v[40:41], off
	v_mul_f32_e32 v11, v25, v25
	v_fmac_f32_e32 v11, v24, v24
	v_fmac_f32_e32 v11, v26, v26
	v_fmac_f32_e32 v11, v27, v27
	v_cndmask_b32_e64 v2, v15, v16, s[6:7]
	v_lshlrev_b32_e32 v2, 2, v2
	v_cmp_lt_i32_e64 s[6:7], v18, v17
	s_waitcnt vmcnt(3)
	v_cvt_pk_bf16_f32 v42, v28, v29
	v_cvt_pk_bf16_f32 v43, v30, v31
	global_store_dwordx2 v[12:13], v[42:43], off offset:512
	s_waitcnt lgkmcnt(0)
	v_mul_f32_e32 v23, v29, v29
	v_fmac_f32_e32 v23, v28, v28
	v_fmac_f32_e32 v23, v30, v30
	v_fmac_f32_e32 v23, v31, v31
	v_add_f32_e32 v11, v11, v23
	s_waitcnt vmcnt(3)
	v_cvt_pk_bf16_f32 v44, v32, v33
	v_cvt_pk_bf16_f32 v45, v34, v35
	global_store_dwordx2 v[12:13], v[44:45], off offset:1024
	v_mul_f32_e32 v23, v33, v33
	v_fmac_f32_e32 v23, v32, v32
	v_fmac_f32_e32 v23, v34, v34
	v_fmac_f32_e32 v23, v35, v35
	v_add_f32_e32 v11, v11, v23
	s_waitcnt vmcnt(3)
	v_mul_f32_e32 v23, v37, v37
	v_fmac_f32_e32 v23, v36, v36
	v_fmac_f32_e32 v23, v38, v38
	v_fmac_f32_e32 v23, v39, v39
	v_add_f32_e32 v11, v11, v23
	ds_bpermute_b32 v2, v2, v11
	v_cndmask_b32_e64 v23, v15, v18, s[6:7]
	v_lshlrev_b32_e32 v23, 2, v23
	v_cmp_lt_i32_e64 s[6:7], v19, v17
	v_cvt_pk_bf16_f32 v24, v36, v37
	s_waitcnt lgkmcnt(0)
	v_add_f32_e32 v2, v11, v2
	ds_bpermute_b32 v11, v23, v2
	v_cndmask_b32_e64 v23, v15, v19, s[6:7]
	v_lshlrev_b32_e32 v23, 2, v23
	v_cmp_lt_i32_e64 s[6:7], v20, v17
	v_cvt_pk_bf16_f32 v25, v38, v39
	s_waitcnt lgkmcnt(0)
	v_add_f32_e32 v2, v2, v11
	ds_bpermute_b32 v11, v23, v2
	v_cndmask_b32_e64 v23, v15, v20, s[6:7]
	v_lshlrev_b32_e32 v23, 2, v23
	v_cmp_lt_i32_e64 s[6:7], v21, v17
	global_store_dwordx2 v[12:13], v[24:25], off offset:1536
	s_waitcnt lgkmcnt(0)
	v_add_f32_e32 v2, v2, v11
	ds_bpermute_b32 v11, v23, v2
	v_cndmask_b32_e64 v23, v15, v21, s[6:7]
	v_lshlrev_b32_e32 v23, 2, v23
	v_cmp_lt_i32_e64 s[6:7], v22, v17
	s_waitcnt lgkmcnt(0)
	v_add_f32_e32 v2, v2, v11
	ds_bpermute_b32 v11, v23, v2
	v_cndmask_b32_e64 v23, v15, v22, s[6:7]
	s_mov_b64 s[6:7], s[24:25]
	s_waitcnt lgkmcnt(0)
	v_add_f32_e32 v11, v2, v11
	v_lshlrev_b32_e32 v2, 2, v23
	ds_bpermute_b32 v23, v2, v11
	s_and_saveexec_b64 s[28:29], vcc
	s_cbranch_execz .LBB0_27
	s_waitcnt lgkmcnt(0)
	v_add_f32_e32 v2, v11, v23
	v_fmamk_f32 v2, v2, 0x3a800000, v1
	v_mul_f32_e32 v11, 0x4b800000, v2
	v_cmp_gt_f32_e64 s[6:7], s17, v2
	s_nop 1
	v_cndmask_b32_e64 v2, v2, v11, s[6:7]
	v_rsq_f32_e32 v2, v2
	s_nop 0
	v_mul_f32_e32 v11, 0x45800000, v2
	v_cndmask_b32_e64 v2, v2, v11, s[6:7]
	s_or_b64 s[6:7], s[24:25], exec
